# mixers A/D shared qpos-ktf distance (v13) with s_nop padding after both regions so all later code sits at the same byte addresses as the previous best
# speedup vs baseline: 1.0086x; 1.0086x over previous
; __device__ __forceinline__ unsigned cvtpk(float lo, float hi) { f32x2_t v = {lo, hi}; bf16x2_t b = __builtin_convertvector(v, bf16x2_t); return __builtin_bit_cast(unsigned, b); }
; template <int DV>
; __device__ __forceinline__ void store_o(const f32x16 (&o)[DV / 32], float sc, bf16_t* Op, int os, int lane) {
;     const int r32 = lane & 31, hi = lane >> 5;
;     bf16_t* rowp = Op + (size_t)r32 * os + 4 * hi;
; #pragma unroll
;     for (int i = 0; i < DV / 32; ++i)
; #pragma unroll
;         for (int rq = 0; rq < 4; ++rq) { u32x2 w; w.x = cvtpk(o[i][4 * rq] * sc, o[i][4 * rq + 1] * sc); w.y = cvtpk(o[i][4 * rq + 2] * sc, o[i][4 * rq + 3] * sc);
;             *(u32x2*)(rowp + 32 * i + 8 * rq) = w; }
; }
; __device__ __forceinline__ void attn_D2(const Ctx& a, LAS unsigned char* lds, int wave_s) {
;     ...
;         store_o<64>(o, 1.f / l, Qp, 512, lane);
;         if (hi == 0) LSE[((size_t)g * MROWS + (size_t)b * SEQ + p0 + r32) * 8 + h] = m + log2f(l);
.LBB0_417:
	ds_bpermute_b32 v34, v80, v83
	s_waitcnt lgkmcnt(0)
	s_barrier
	s_waitcnt lgkmcnt(0)
	v_add_f32_e32 v34, v83, v34
	v_div_scale_f32 v35, s[24:25], v34, v34, 1.0
	v_rcp_f32_e32 v36, v35
	s_nop 0
	v_fma_f32 v37, -v35, v36, 1.0
	v_fmac_f32_e32 v36, v37, v36
	v_div_scale_f32 v37, vcc, 1.0, v34, 1.0
	v_mul_f32_e32 v38, v37, v36
	v_fma_f32 v39, -v35, v38, v37
	v_fmac_f32_e32 v38, v39, v36
	v_fma_f32 v35, -v35, v38, v37
	v_div_fmas_f32 v35, v35, v36, v38
	v_div_fixup_f32 v36, v35, v34, 1.0
	v_pk_mul_f32 v[18:19], v[18:19], v[36:37] op_sel_hi:[1,0]
	v_pk_mul_f32 v[20:21], v[20:21], v[36:37] op_sel_hi:[1,0]
	v_pk_mul_f32 v[2:3], v[2:3], v[36:37] op_sel_hi:[1,0]
	v_pk_mul_f32 v[4:5], v[4:5], v[36:37] op_sel_hi:[1,0]
	v_lshl_add_u64 v[38:39], v[70:71], 1, v[74:75]
	v_cvt_pk_bf16_f32 v18, v18, v19
	v_cvt_pk_bf16_f32 v19, v20, v21
	v_cvt_pk_bf16_f32 v2, v2, v3
	v_cvt_pk_bf16_f32 v3, v4, v5
	global_store_dwordx2 v[38:39], v[18:19], off
	v_pk_mul_f32 v[18:19], v[22:23], v[36:37] op_sel_hi:[1,0]
	v_pk_mul_f32 v[20:21], v[24:25], v[36:37] op_sel_hi:[1,0]
	global_store_dwordx2 v[38:39], v[2:3], off offset:64
	v_pk_mul_f32 v[2:3], v[6:7], v[36:37] op_sel_hi:[1,0]
	v_pk_mul_f32 v[4:5], v[8:9], v[36:37] op_sel_hi:[1,0]
	v_cvt_pk_bf16_f32 v18, v18, v19
	v_cvt_pk_bf16_f32 v19, v20, v21
	v_cvt_pk_bf16_f32 v2, v2, v3
	v_cvt_pk_bf16_f32 v3, v4, v5
	global_store_dwordx2 v[38:39], v[18:19], off offset:16
	v_pk_mul_f32 v[18:19], v[26:27], v[36:37] op_sel_hi:[1,0]
	v_pk_mul_f32 v[20:21], v[28:29], v[36:37] op_sel_hi:[1,0]
	global_store_dwordx2 v[38:39], v[2:3], off offset:80
	v_pk_mul_f32 v[2:3], v[10:11], v[36:37] op_sel_hi:[1,0]
	v_pk_mul_f32 v[4:5], v[12:13], v[36:37] op_sel_hi:[1,0]
	v_cvt_pk_bf16_f32 v18, v18, v19
	v_cvt_pk_bf16_f32 v19, v20, v21
	v_cvt_pk_bf16_f32 v2, v2, v3
	v_cvt_pk_bf16_f32 v3, v4, v5
	global_store_dwordx2 v[38:39], v[18:19], off offset:32
	v_pk_mul_f32 v[18:19], v[30:31], v[36:37] op_sel_hi:[1,0]
	v_pk_mul_f32 v[20:21], v[32:33], v[36:37] op_sel_hi:[1,0]
	global_store_dwordx2 v[38:39], v[2:3], off offset:96
	v_pk_mul_f32 v[2:3], v[14:15], v[36:37] op_sel_hi:[1,0]
	v_pk_mul_f32 v[4:5], v[16:17], v[36:37] op_sel_hi:[1,0]
	v_cvt_pk_bf16_f32 v18, v18, v19
	v_cvt_pk_bf16_f32 v19, v20, v21
	v_cvt_pk_bf16_f32 v2, v2, v3
	v_cvt_pk_bf16_f32 v3, v4, v5
	global_store_dwordx2 v[38:39], v[18:19], off offset:48
	global_store_dwordx2 v[38:39], v[2:3], off offset:112
	s_and_saveexec_b64 s[24:25], s[0:1]
	s_cbranch_execz .LBB0_399
	s_mov_b32 s10, 0x800000
	v_cmp_gt_f32_e32 vcc, s10, v34
	v_mov_b32_e32 v2, 0x42000000
	s_mul_hi_i32 s10, s18, 0x14000
	v_cndmask_b32_e64 v3, 0, 32, vcc
	v_ldexp_f32 v3, v34, v3
	v_log_f32_e32 v3, v3
	v_cndmask_b32_e32 v2, 0, v2, vcc
	s_mul_i32 s18, s18, 0x14000
	s_add_u32 s6, s18, s6
	v_sub_f32_e32 v2, v3, v2
	v_add_f32_e32 v4, v82, v2
	s_addc_u32 s7, s10, s7
	v_mov_b32_e32 v2, s23
	v_or3_b32 v3, s7, 0, 0
	v_or3_b32 v2, s6, v66, v2
	v_lshlrev_b64 v[2:3], 5, v[2:3]
	v_lshl_add_u64 v[2:3], s[4:5], 0, v[2:3]
	s_lshl_b32 s10, s16, 2
	v_lshl_add_u64 v[2:3], v[2:3], 0, s[10:11]
	global_store_dword v[2:3], v4, off
	s_branch .LBB0_399
	s_nop 0
	s_nop 0
	s_nop 0
	s_nop 0
	s_nop 0
	s_nop 0
	s_nop 0
	s_nop 0
	s_nop 0
	s_nop 0
	s_nop 0
	s_nop 0
	s_nop 0
	s_nop 0

; #define BA_DMA(t_, s_) __builtin_amdgcn_global_load_lds((const unsigned*)(src + (size_t)(t_) * 2048), (LAS unsigned*)(lds + (s_) * 8192 + dsto), 16, 0, 0)
; #define BA_DMA(t_, s_) do { __builtin_amdgcn_global_load_lds((const unsigned*)(srcA + (size_t)(t_) * 2048), (LAS unsigned*)(lds + (s_) * 16384 + dsto), 16, 0, 0); \
;         __builtin_amdgcn_global_load_lds((const unsigned*)(srcB + (size_t)(t_) * 2048), (LAS unsigned*)(lds + (s_) * 16384 + 8192 + dsto), 16, 0, 0); } while (0)
; template <class BiasF> ...
;     ...
;     for (int i = 0; i < n; ++i) {
;         const int kt = (T0 + i) * 32;
;         if (i + 1 < n) asm volatile("s_waitcnt vmcnt(1)" ::: "memory"); else asm volatile("s_waitcnt vmcnt(0)" ::: "memory");
;         asm volatile("s_waitcnt lgkmcnt(0)\n\ts_barrier" ::: "memory");
;         const int s2 = s == 0 ? 2 : s - 1;
;         if (i + 2 < n) BA_DMA(T0 + i + 2, s2);
;     ...
;         s = s == 2 ? 0 : s + 1;
;     }
.LBB0_680:
	s_add_i32 s6, s26, 1
	s_cmp_lg_u32 s26, 2
	s_cselect_b32 s26, s6, 0
	v_lshl_add_u64 v[74:75], v[74:75], 0, s[64:65]
	s_andn2_b64 vcc, exec, s[4:5]
	s_add_i32 s10, s10, 32
	s_cbranch_vccz .LBB0_665
	s_mov_b32 s30, s29
	s_branch .LBB0_670
	s_nop 0
	s_nop 0
	s_nop 0
	s_nop 0
	s_nop 0
	s_nop 0
	s_nop 0
	s_nop 0
	s_nop 0
	s_nop 0
	s_nop 0
	s_nop 0
	s_nop 0
	s_nop 0
